# plus 64-bit accumulator zeroing, ff1 relu without canonicalize, conv LN DPP sums
# baseline (speedup 1.0000x reference)
.LBB0_137:
	v_mov_b64_e32 v[0:1], 0xa00
	s_add_u32 s20, s86, s16
	v_cmp_lt_i64_e32 vcc, s[8:9], v[0:1]
	s_addc_u32 s21, s87, s17
	s_and_b64 s[8:9], vcc, exec
	s_cselect_b32 s13, s21, s5
	s_cselect_b32 s15, s20, s4
	s_add_u32 s22, s25, s18
	s_addc_u32 s23, s34, s19
	s_and_b64 s[8:9], vcc, exec
	s_cselect_b32 s26, s23, s7
	s_cselect_b32 s28, s22, s6
	s_add_u32 s4, s4, 0x40080
	s_addc_u32 s5, s5, 0
	s_add_u32 s29, s6, 0x100
	v_mov_b32_e32 v0, 0
	s_addc_u32 s69, s7, 0
	s_mov_b32 s70, -2
	v_mov_b64_e32 v[0:1], 0
	v_mov_b64_e32 v[2:3], 0
	v_mov_b64_e32 v[4:5], 0
	v_mov_b64_e32 v[6:7], 0
	v_mov_b64_e32 v[8:9], 0
	v_mov_b64_e32 v[10:11], 0
	v_mov_b64_e32 v[12:13], 0
	v_mov_b64_e32 v[14:15], 0
	v_mov_b64_e32 v[16:17], 0
	v_mov_b64_e32 v[18:19], 0
	v_mov_b64_e32 v[20:21], 0
	v_mov_b64_e32 v[22:23], 0
	v_mov_b64_e32 v[24:25], 0
	v_mov_b64_e32 v[26:27], 0
	v_mov_b64_e32 v[28:29], 0
	v_mov_b64_e32 v[30:31], 0
	v_mov_b64_e32 v[32:33], 0
	v_mov_b64_e32 v[34:35], 0
	v_mov_b64_e32 v[36:37], 0
	v_mov_b64_e32 v[38:39], 0
	v_mov_b64_e32 v[40:41], 0
	v_mov_b64_e32 v[42:43], 0
	v_mov_b64_e32 v[44:45], 0
	v_mov_b64_e32 v[46:47], 0
	v_mov_b64_e32 v[48:49], 0
	v_mov_b64_e32 v[50:51], 0
	v_mov_b64_e32 v[52:53], 0
	v_mov_b64_e32 v[54:55], 0
	v_mov_b64_e32 v[56:57], 0
	v_mov_b64_e32 v[58:59], 0
	v_mov_b64_e32 v[60:61], 0
	v_mov_b64_e32 v[62:63], 0
	v_mov_b64_e32 v[64:65], 0
	v_mov_b64_e32 v[66:67], 0
	v_mov_b64_e32 v[68:69], 0
	v_mov_b64_e32 v[70:71], 0
	v_mov_b64_e32 v[72:73], 0
	v_mov_b64_e32 v[74:75], 0
	v_mov_b64_e32 v[76:77], 0
	v_mov_b64_e32 v[78:79], 0
	v_mov_b64_e32 v[80:81], 0
	v_mov_b64_e32 v[82:83], 0
	v_mov_b64_e32 v[84:85], 0
	v_mov_b64_e32 v[86:87], 0
	v_mov_b64_e32 v[88:89], 0
	v_mov_b64_e32 v[90:91], 0
	v_mov_b64_e32 v[92:93], 0
	v_mov_b64_e32 v[94:95], 0
	v_mov_b64_e32 v[96:97], 0
	v_mov_b64_e32 v[98:99], 0
	v_mov_b64_e32 v[100:101], 0
	v_mov_b64_e32 v[102:103], 0
	v_mov_b64_e32 v[104:105], 0
	v_mov_b64_e32 v[106:107], 0
	v_mov_b64_e32 v[108:109], 0
	v_mov_b64_e32 v[110:111], 0
	v_mov_b64_e32 v[112:113], 0
	v_mov_b64_e32 v[114:115], 0
	v_mov_b64_e32 v[116:117], 0
	v_mov_b64_e32 v[118:119], 0
	v_mov_b64_e32 v[120:121], 0
	v_mov_b64_e32 v[122:123], 0
	v_mov_b64_e32 v[124:125], 0
	v_mov_b64_e32 v[126:127], 0

.LBB0_446:
	v_cmp_lt_i64_e32 vcc, s[14:15], v[198:199]
	s_add_u32 s14, s30, s10
	s_addc_u32 s15, s31, s11
	s_and_b64 s[16:17], vcc, exec
	s_cselect_b32 s0, s15, s21
	s_cselect_b32 s5, s14, s20
	s_add_u32 s16, s86, s12
	s_addc_u32 s17, s87, s13
	s_and_b64 s[24:25], vcc, exec
	s_cselect_b32 s7, s17, s23
	s_cselect_b32 s9, s16, s22
	s_add_u32 s20, s20, 0x40080
	s_addc_u32 s21, s21, 0
	s_add_u32 s65, s22, 0x100
	v_mov_b32_e32 v0, 0
	s_addc_u32 s66, s23, 0
	s_mov_b32 s67, -2
	v_mov_b64_e32 v[0:1], 0
	v_mov_b64_e32 v[2:3], 0
	v_mov_b64_e32 v[4:5], 0
	v_mov_b64_e32 v[6:7], 0
	v_mov_b64_e32 v[8:9], 0
	v_mov_b64_e32 v[10:11], 0
	v_mov_b64_e32 v[12:13], 0
	v_mov_b64_e32 v[14:15], 0
	v_mov_b64_e32 v[16:17], 0
	v_mov_b64_e32 v[18:19], 0
	v_mov_b64_e32 v[20:21], 0
	v_mov_b64_e32 v[22:23], 0
	v_mov_b64_e32 v[24:25], 0
	v_mov_b64_e32 v[26:27], 0
	v_mov_b64_e32 v[28:29], 0
	v_mov_b64_e32 v[30:31], 0
	v_mov_b64_e32 v[32:33], 0
	v_mov_b64_e32 v[34:35], 0
	v_mov_b64_e32 v[36:37], 0
	v_mov_b64_e32 v[38:39], 0
	v_mov_b64_e32 v[40:41], 0
	v_mov_b64_e32 v[42:43], 0
	v_mov_b64_e32 v[44:45], 0
	v_mov_b64_e32 v[46:47], 0
	v_mov_b64_e32 v[48:49], 0
	v_mov_b64_e32 v[50:51], 0
	v_mov_b64_e32 v[52:53], 0
	v_mov_b64_e32 v[54:55], 0
	v_mov_b64_e32 v[56:57], 0
	v_mov_b64_e32 v[58:59], 0
	v_mov_b64_e32 v[60:61], 0
	v_mov_b64_e32 v[62:63], 0
	v_mov_b64_e32 v[64:65], 0
	v_mov_b64_e32 v[66:67], 0
	v_mov_b64_e32 v[68:69], 0
	v_mov_b64_e32 v[70:71], 0
	v_mov_b64_e32 v[72:73], 0
	v_mov_b64_e32 v[74:75], 0
	v_mov_b64_e32 v[76:77], 0
	v_mov_b64_e32 v[78:79], 0
	v_mov_b64_e32 v[80:81], 0
	v_mov_b64_e32 v[82:83], 0
	v_mov_b64_e32 v[84:85], 0
	v_mov_b64_e32 v[86:87], 0
	v_mov_b64_e32 v[88:89], 0
	v_mov_b64_e32 v[90:91], 0
	v_mov_b64_e32 v[92:93], 0
	v_mov_b64_e32 v[94:95], 0
	v_mov_b64_e32 v[96:97], 0
	v_mov_b64_e32 v[98:99], 0
	v_mov_b64_e32 v[100:101], 0
	v_mov_b64_e32 v[102:103], 0
	v_mov_b64_e32 v[104:105], 0
	v_mov_b64_e32 v[106:107], 0
	v_mov_b64_e32 v[108:109], 0
	v_mov_b64_e32 v[110:111], 0
	v_mov_b64_e32 v[112:113], 0
	v_mov_b64_e32 v[114:115], 0
	v_mov_b64_e32 v[116:117], 0
	v_mov_b64_e32 v[118:119], 0
	v_mov_b64_e32 v[120:121], 0
	v_mov_b64_e32 v[122:123], 0
	v_mov_b64_e32 v[124:125], 0
	v_mov_b64_e32 v[126:127], 0

.LBB0_499:
	v_add_u32_e32 v9, s4, v73
	ds_read_b128 v[10:13], v9
	s_addk_i32 s4, 0x400
	s_cmpk_eq_i32 s4, 0x2000
	s_waitcnt lgkmcnt(0)
	v_add_f32_e32 v9, v10, v11
	v_add_f32_e32 v9, v9, v12
	v_add_f32_e32 v9, v9, v13
	s_nop 1
	v_add_f32_dpp v9, v9, v9 quad_perm:[1,0,3,2] row_mask:0xf bank_mask:0xf
	s_nop 1
	v_add_f32_dpp v9, v9, v9 quad_perm:[2,3,0,1] row_mask:0xf bank_mask:0xf
	s_nop 1
	v_add_f32_dpp v9, v9, v9 row_ror:4 row_mask:0xf bank_mask:0xf
	s_nop 1
	v_add_f32_dpp v9, v9, v9 row_ror:8 row_mask:0xf bank_mask:0xf
	s_nop 1
	v_add_f32_dpp v9, v9, v9 row_bcast:15 row_mask:0xa bank_mask:0xf
	s_nop 1
	v_add_f32_dpp v9, v9, v9 row_bcast:31 row_mask:0xc bank_mask:0xf
	s_nop 1
	v_readlane_b32 s2, v9, 63
	s_nop 1
	v_mov_b32_e32 v9, s2
	v_mul_f32_e32 v14, 0x3b800000, v9
	v_pk_add_f32 v[10:11], v[10:11], v[14:15] op_sel_hi:[1,0] neg_lo:[0,1] neg_hi:[0,1]
	v_pk_add_f32 v[12:13], v[12:13], v[14:15] op_sel_hi:[1,0] neg_lo:[0,1] neg_hi:[0,1]
	v_pk_mul_f32 v[14:15], v[10:11], v[10:11]
	v_pk_mul_f32 v[16:17], v[12:13], v[12:13]
	v_add_f32_e32 v9, v14, v15
	v_add_f32_e32 v9, v16, v9
	v_add_f32_e32 v9, v17, v9
	s_nop 1
	v_add_f32_dpp v9, v9, v9 quad_perm:[1,0,3,2] row_mask:0xf bank_mask:0xf
	s_nop 1
	v_add_f32_dpp v9, v9, v9 quad_perm:[2,3,0,1] row_mask:0xf bank_mask:0xf
	s_nop 1
	v_add_f32_dpp v9, v9, v9 row_ror:4 row_mask:0xf bank_mask:0xf
	s_nop 1
	v_add_f32_dpp v9, v9, v9 row_ror:8 row_mask:0xf bank_mask:0xf
	s_nop 1
	v_add_f32_dpp v9, v9, v9 row_bcast:15 row_mask:0xa bank_mask:0xf
	s_nop 1
	v_add_f32_dpp v9, v9, v9 row_bcast:31 row_mask:0xc bank_mask:0xf
	s_nop 1
	v_readlane_b32 s2, v9, 63
	s_nop 1
	v_mov_b32_e32 v9, s2
	v_fmamk_f32 v9, v9, 0x3b800000, v194
	v_cmp_gt_f32_e64 s[2:3], s11, v9
	v_mul_f32_e32 v14, 0x4b800000, v9
	s_nop 0
	v_cndmask_b32_e64 v9, v9, v14, s[2:3]
	v_rsq_f32_e32 v9, v9
	s_nop 0
	v_mul_f32_e32 v14, 0x45800000, v9
	v_cndmask_b32_e64 v14, v9, v14, s[2:3]
	v_pk_mul_f32 v[10:11], v[10:11], v[14:15] op_sel_hi:[1,0]
	v_pk_mul_f32 v[12:13], v[12:13], v[14:15] op_sel_hi:[1,0]
	v_pk_fma_f32 v[10:11], v[0:1], v[10:11], v[4:5]
	v_pk_fma_f32 v[12:13], v[2:3], v[12:13], v[6:7]
	v_mul_f32_e32 v9, 0xbfb8aa3b, v10
	v_exp_f32_e32 v9, v9
	s_nop 0
	v_add_f32_e32 v9, 1.0, v9
	v_rcp_f32_e32 v14, v9
	v_mul_f32_e32 v9, 0xbfb8aa3b, v11
	v_exp_f32_e32 v9, v9
	s_nop 0
	v_add_f32_e32 v9, 1.0, v9
	v_rcp_f32_e32 v15, v9
	v_mul_f32_e32 v9, 0xbfb8aa3b, v12
	v_exp_f32_e32 v9, v9
	v_pk_mul_f32 v[10:11], v[10:11], v[14:15]
	s_nop 0
	v_cvt_pk_bf16_f32 v10, v10, v11
	v_add_f32_e32 v9, 1.0, v9
	v_rcp_f32_e32 v14, v9
	v_mul_f32_e32 v9, 0xbfb8aa3b, v13
	v_exp_f32_e32 v9, v9
	s_nop 0
	v_add_f32_e32 v9, 1.0, v9
	v_rcp_f32_e32 v15, v9
	v_ashrrev_i32_e32 v9, 31, v8
	v_pk_mul_f32 v[12:13], v[12:13], v[14:15]
	s_nop 0
	v_cvt_pk_bf16_f32 v11, v12, v13
	v_lshlrev_b64 v[12:13], 11, v[8:9]
	v_lshl_add_u64 v[12:13], v[22:23], 0, v[12:13]
	v_add_u32_e32 v8, 1, v8
	global_store_dwordx2 v[12:13], v[10:11], off
	s_cbranch_scc0 .LBB0_499
	v_readlane_b32 s2, v253, 0
	s_add_i32 s0, s0, s2
	s_cmpk_gt_i32 s0, 0x4ff
	v_add_u32_e32 v72, s8, v72
	s_barrier
	s_cbranch_scc0 .LBB0_480

.LBB0_894:
	s_mov_b32 s6, s75
	s_add_i32 s75, s75, 1
	s_cmp_lt_u32 s6, 3
	s_cselect_b64 s[24:25], -1, 0
	s_lshl_b32 s6, s75, 21
	s_mov_b64 s[28:29], s[16:17]
	s_add_u32 s16, s0, s6
	s_addc_u32 s17, s71, 0
	s_and_b64 s[6:7], s[24:25], exec
	s_cselect_b32 s22, s2, s22
	s_mov_b64 s[26:27], s[18:19]
	s_cselect_b32 s21, s17, s21
	s_cselect_b32 s20, s16, s20
	s_cselect_b32 s23, s3, s23
	s_add_u32 s18, s86, s22
	s_addc_u32 s19, s87, s23
	s_and_b64 s[6:7], s[24:25], exec
	v_readlane_b32 s16, v253, 1
	s_cselect_b32 s6, s19, s27
	s_cselect_b32 s7, s18, s26
	v_readlane_b32 s17, v253, 2
	s_add_u32 s16, s16, s20
	s_addc_u32 s17, s17, s21
	s_and_b64 s[30:31], s[24:25], exec
	s_cselect_b32 s77, s17, s29
	s_cselect_b32 s78, s16, s28
	s_add_u32 s26, s26, 0x40080
	s_addc_u32 s27, s27, 0
	s_add_u32 s79, s28, 0x100
	v_mov_b32_e32 v0, 0
	s_addc_u32 s80, s29, 0
	s_mov_b32 s81, -2
	v_mov_b64_e32 v[0:1], 0
	v_mov_b64_e32 v[2:3], 0
	v_mov_b64_e32 v[4:5], 0
	v_mov_b64_e32 v[6:7], 0
	v_mov_b64_e32 v[8:9], 0
	v_mov_b64_e32 v[10:11], 0
	v_mov_b64_e32 v[12:13], 0
	v_mov_b64_e32 v[14:15], 0
	v_mov_b64_e32 v[16:17], 0
	v_mov_b64_e32 v[18:19], 0
	v_mov_b64_e32 v[20:21], 0
	v_mov_b64_e32 v[22:23], 0
	v_mov_b64_e32 v[24:25], 0
	v_mov_b64_e32 v[26:27], 0
	v_mov_b64_e32 v[28:29], 0
	v_mov_b64_e32 v[30:31], 0
	v_mov_b64_e32 v[32:33], 0
	v_mov_b64_e32 v[34:35], 0
	v_mov_b64_e32 v[36:37], 0
	v_mov_b64_e32 v[38:39], 0
	v_mov_b64_e32 v[40:41], 0
	v_mov_b64_e32 v[42:43], 0
	v_mov_b64_e32 v[44:45], 0
	v_mov_b64_e32 v[46:47], 0
	v_mov_b64_e32 v[48:49], 0
	v_mov_b64_e32 v[50:51], 0
	v_mov_b64_e32 v[52:53], 0
	v_mov_b64_e32 v[54:55], 0
	v_mov_b64_e32 v[56:57], 0
	v_mov_b64_e32 v[58:59], 0
	v_mov_b64_e32 v[60:61], 0
	v_mov_b64_e32 v[62:63], 0
	v_mov_b64_e32 v[64:65], 0
	v_mov_b64_e32 v[66:67], 0
	v_mov_b64_e32 v[68:69], 0
	v_mov_b64_e32 v[70:71], 0
	v_mov_b64_e32 v[72:73], 0
	v_mov_b64_e32 v[74:75], 0
	v_mov_b64_e32 v[76:77], 0
	v_mov_b64_e32 v[78:79], 0
	v_mov_b64_e32 v[80:81], 0
	v_mov_b64_e32 v[82:83], 0
	v_mov_b64_e32 v[84:85], 0
	v_mov_b64_e32 v[86:87], 0
	v_mov_b64_e32 v[88:89], 0
	v_mov_b64_e32 v[90:91], 0
	v_mov_b64_e32 v[92:93], 0
	v_mov_b64_e32 v[94:95], 0
	v_mov_b64_e32 v[96:97], 0
	v_mov_b64_e32 v[98:99], 0
	v_mov_b64_e32 v[100:101], 0
	v_mov_b64_e32 v[102:103], 0
	v_mov_b64_e32 v[104:105], 0
	v_mov_b64_e32 v[106:107], 0
	v_mov_b64_e32 v[108:109], 0
	v_mov_b64_e32 v[110:111], 0
	v_mov_b64_e32 v[112:113], 0
	v_mov_b64_e32 v[114:115], 0
	v_mov_b64_e32 v[116:117], 0
	v_mov_b64_e32 v[118:119], 0
	v_mov_b64_e32 v[120:121], 0
	v_mov_b64_e32 v[122:123], 0
	v_mov_b64_e32 v[124:125], 0
	v_mov_b64_e32 v[126:127], 0

.LBB0_913:
	v_lshrrev_b32_e32 v10, 1, v0
	v_and_b32_e32 v10, 24, v10
	v_and_b32_e32 v1, 15, v0
	v_lshlrev_b32_e32 v192, 1, v10
	v_lshlrev_b32_e32 v0, 2, v0
	v_lshl_or_b32 v201, s0, 6, v1
	v_lshl_or_b32 v1, v1, 6, v192
	s_lshl_b32 s0, s0, 13
	v_and_b32_e32 v0, 32, v0
	v_bitop3_b32 v243, v1, s0, v0 bitop3:0xde
	s_lshl_b32 s0, s4, 5
	v_mov_b32_e32 v209, v193
	s_and_b32 s6, s0, 0x60
	v_lshl_add_u64 v[2:3], s[22:23], 0, v[208:209]
	v_mov_b32_e32 v213, v193
	s_lshl_b32 s0, s6, 7
	s_add_i32 s75, s66, 0x18000
	v_lshl_add_u64 v[4:5], s[22:23], 0, v[212:213]
	v_mov_b32_e32 v207, v193
	v_bitop3_b32 v244, v1, s0, v0 bitop3:0xde
	v_lshl_add_u64 v[0:1], v[2:3], 0, s[94:95]
	s_mov_b32 m0, s75
	s_add_i32 s76, s66, 0x1a000
	v_lshl_add_u64 v[6:7], s[24:25], 0, v[206:207]
	v_mov_b32_e32 v211, v193
	s_waitcnt vmcnt(4)
	s_barrier
	global_load_lds_dwordx4 v[0:1], off
	v_lshl_add_u64 v[0:1], v[4:5], 0, s[94:95]
	s_mov_b32 m0, s76
	s_add_i32 s77, s66, 0x8000
	s_add_i32 s78, s66, 0xa000
	v_lshl_add_u64 v[8:9], s[24:25], 0, v[210:211]
	global_load_lds_dwordx4 v[0:1], off
	v_lshl_add_u64 v[0:1], v[6:7], 0, s[94:95]
	s_mov_b32 m0, s77
	s_add_u32 s4, s22, 0x40080
	global_load_lds_dwordx4 v[0:1], off
	v_lshl_add_u64 v[0:1], v[8:9], 0, s[94:95]
	s_mov_b32 m0, s78
	s_addc_u32 s5, s23, 0
	s_add_i32 s79, s66, 0x1c000
	global_load_lds_dwordx4 v[0:1], off
	v_lshl_add_u64 v[0:1], s[4:5], 0, v[208:209]
	s_mov_b32 m0, s79
	s_add_i32 s80, s66, 0x1e000
	global_load_lds_dwordx4 v[0:1], off
	v_lshl_add_u64 v[0:1], s[4:5], 0, v[212:213]
	s_mov_b32 m0, s80
	s_lshl_b32 s0, s6, 1
	global_load_lds_dwordx4 v[0:1], off
	v_lshlrev_b32_e32 v0, 8, v201
	v_ashrrev_i32_e32 v1, 31, v0
	v_lshl_add_u64 v[0:1], v[0:1], 1, s[10:11]
	s_add_u32 s81, s2, 0xa000000
	s_waitcnt vmcnt(6)
	v_lshl_add_u64 v[0:1], v[0:1], 0, s[0:1]
	s_addc_u32 s82, s3, 0
	v_lshl_add_u64 v[214:215], v[0:1], 0, v[192:193]
	s_add_u32 s83, s16, s43
	v_mov_b32_e32 v0, 0
	s_addc_u32 s88, s17, s44
	s_mov_b32 s17, 0
	s_lshl_b32 s16, s6, 1
	v_lshlrev_b32_e32 v192, 1, v10
	s_mov_b32 s5, 0
	v_mov_b64_e32 v[0:1], 0
	v_mov_b64_e32 v[2:3], 0
	v_mov_b64_e32 v[4:5], 0
	v_mov_b64_e32 v[6:7], 0
	v_mov_b64_e32 v[8:9], 0
	v_mov_b64_e32 v[10:11], 0
	v_mov_b64_e32 v[12:13], 0
	v_mov_b64_e32 v[14:15], 0
	v_mov_b64_e32 v[16:17], 0
	v_mov_b64_e32 v[18:19], 0
	v_mov_b64_e32 v[20:21], 0
	v_mov_b64_e32 v[22:23], 0
	v_mov_b64_e32 v[24:25], 0
	v_mov_b64_e32 v[26:27], 0
	v_mov_b64_e32 v[28:29], 0
	v_mov_b64_e32 v[30:31], 0
	v_mov_b64_e32 v[32:33], 0
	v_mov_b64_e32 v[34:35], 0
	v_mov_b64_e32 v[36:37], 0
	v_mov_b64_e32 v[38:39], 0
	v_mov_b64_e32 v[40:41], 0
	v_mov_b64_e32 v[42:43], 0
	v_mov_b64_e32 v[44:45], 0
	v_mov_b64_e32 v[46:47], 0
	v_mov_b64_e32 v[48:49], 0
	v_mov_b64_e32 v[50:51], 0
	v_mov_b64_e32 v[52:53], 0
	v_mov_b64_e32 v[54:55], 0
	v_mov_b64_e32 v[56:57], 0
	v_mov_b64_e32 v[58:59], 0
	v_mov_b64_e32 v[60:61], 0
	v_mov_b64_e32 v[62:63], 0
	v_mov_b64_e32 v[64:65], 0
	v_mov_b64_e32 v[66:67], 0
	v_mov_b64_e32 v[68:69], 0
	v_mov_b64_e32 v[70:71], 0
	v_mov_b64_e32 v[72:73], 0
	v_mov_b64_e32 v[74:75], 0
	v_mov_b64_e32 v[76:77], 0
	v_mov_b64_e32 v[78:79], 0
	v_mov_b64_e32 v[80:81], 0
	v_mov_b64_e32 v[82:83], 0
	v_mov_b64_e32 v[84:85], 0
	v_mov_b64_e32 v[86:87], 0
	v_mov_b64_e32 v[88:89], 0
	v_mov_b64_e32 v[90:91], 0
	v_mov_b64_e32 v[92:93], 0
	v_mov_b64_e32 v[94:95], 0
	v_mov_b64_e32 v[96:97], 0
	v_mov_b64_e32 v[98:99], 0
	v_mov_b64_e32 v[100:101], 0
	v_mov_b64_e32 v[102:103], 0
	v_mov_b64_e32 v[104:105], 0
	v_mov_b64_e32 v[106:107], 0
	v_mov_b64_e32 v[108:109], 0
	v_mov_b64_e32 v[110:111], 0
	v_mov_b64_e32 v[112:113], 0
	v_mov_b64_e32 v[114:115], 0
	v_mov_b64_e32 v[116:117], 0
	v_mov_b64_e32 v[118:119], 0
	v_mov_b64_e32 v[120:121], 0
	v_mov_b64_e32 v[122:123], 0
	v_mov_b64_e32 v[124:125], 0
	v_mov_b64_e32 v[126:127], 0
	s_barrier
	s_branch .LBB0_916

.LBB0_952:
	s_cmp_lg_u32 s5, 3
	s_mov_b64 s[22:23], -1
	s_cbranch_scc0 .LBB0_915
	s_and_b64 vcc, exec, s[2:3]
	s_cbranch_vccnz .LBB0_914
	v_mov_b32_e32 v0, 0
	v_mov_b64_e32 v[0:1], 0
	v_mov_b64_e32 v[2:3], 0
	v_mov_b64_e32 v[4:5], 0
	v_mov_b64_e32 v[6:7], 0
	v_mov_b64_e32 v[8:9], 0
	v_mov_b64_e32 v[10:11], 0
	v_mov_b64_e32 v[12:13], 0
	v_mov_b64_e32 v[14:15], 0
	v_mov_b64_e32 v[16:17], 0
	v_mov_b64_e32 v[18:19], 0
	v_mov_b64_e32 v[20:21], 0
	v_mov_b64_e32 v[22:23], 0
	v_mov_b64_e32 v[24:25], 0
	v_mov_b64_e32 v[26:27], 0
	v_mov_b64_e32 v[28:29], 0
	v_mov_b64_e32 v[30:31], 0
	v_mov_b64_e32 v[32:33], 0
	v_mov_b64_e32 v[34:35], 0
	v_mov_b64_e32 v[36:37], 0
	v_mov_b64_e32 v[38:39], 0
	v_mov_b64_e32 v[40:41], 0
	v_mov_b64_e32 v[42:43], 0
	v_mov_b64_e32 v[44:45], 0
	v_mov_b64_e32 v[46:47], 0
	v_mov_b64_e32 v[48:49], 0
	v_mov_b64_e32 v[50:51], 0
	v_mov_b64_e32 v[52:53], 0
	v_mov_b64_e32 v[54:55], 0
	v_mov_b64_e32 v[56:57], 0
	v_mov_b64_e32 v[58:59], 0
	v_mov_b64_e32 v[60:61], 0
	v_mov_b64_e32 v[62:63], 0
	v_mov_b64_e32 v[64:65], 0
	v_mov_b64_e32 v[66:67], 0
	v_mov_b64_e32 v[68:69], 0
	v_mov_b64_e32 v[70:71], 0
	v_mov_b64_e32 v[72:73], 0
	v_mov_b64_e32 v[74:75], 0
	v_mov_b64_e32 v[76:77], 0
	v_mov_b64_e32 v[78:79], 0
	v_mov_b64_e32 v[80:81], 0
	v_mov_b64_e32 v[82:83], 0
	v_mov_b64_e32 v[84:85], 0
	v_mov_b64_e32 v[86:87], 0
	v_mov_b64_e32 v[88:89], 0
	v_mov_b64_e32 v[90:91], 0
	v_mov_b64_e32 v[92:93], 0
	v_mov_b64_e32 v[94:95], 0
	v_mov_b64_e32 v[96:97], 0
	v_mov_b64_e32 v[98:99], 0
	v_mov_b64_e32 v[100:101], 0
	v_mov_b64_e32 v[102:103], 0
	v_mov_b64_e32 v[104:105], 0
	v_mov_b64_e32 v[106:107], 0
	v_mov_b64_e32 v[108:109], 0
	v_mov_b64_e32 v[110:111], 0
	v_mov_b64_e32 v[112:113], 0
	v_mov_b64_e32 v[114:115], 0
	v_mov_b64_e32 v[116:117], 0
	v_mov_b64_e32 v[118:119], 0
	v_mov_b64_e32 v[120:121], 0
	v_mov_b64_e32 v[122:123], 0
	v_mov_b64_e32 v[124:125], 0
	v_mov_b64_e32 v[126:127], 0
	s_branch .LBB0_914

.LBB0_976:
	v_cmp_lt_i64_e32 vcc, s[14:15], v[198:199]
	v_readlane_b32 s14, v254, 25
	v_readlane_b32 s15, v254, 26
	s_add_u32 s14, s14, s10
	s_addc_u32 s15, s15, s11
	s_and_b64 s[16:17], vcc, exec
	s_cselect_b32 s7, s15, s21
	s_cselect_b32 s9, s14, s20
	s_add_u32 s16, s27, s12
	s_addc_u32 s17, s28, s13
	s_and_b64 s[24:25], vcc, exec
	s_cselect_b32 s19, s17, s23
	s_cselect_b32 s64, s16, s22
	s_add_u32 s20, s20, 0x40080
	s_addc_u32 s21, s21, 0
	s_add_u32 s65, s22, 0x100
	v_mov_b32_e32 v0, 0
	s_addc_u32 s66, s23, 0
	s_mov_b32 s67, -2
	v_mov_b64_e32 v[0:1], 0
	v_mov_b64_e32 v[2:3], 0
	v_mov_b64_e32 v[4:5], 0
	v_mov_b64_e32 v[6:7], 0
	v_mov_b64_e32 v[8:9], 0
	v_mov_b64_e32 v[10:11], 0
	v_mov_b64_e32 v[12:13], 0
	v_mov_b64_e32 v[14:15], 0
	v_mov_b64_e32 v[16:17], 0
	v_mov_b64_e32 v[18:19], 0
	v_mov_b64_e32 v[20:21], 0
	v_mov_b64_e32 v[22:23], 0
	v_mov_b64_e32 v[24:25], 0
	v_mov_b64_e32 v[26:27], 0
	v_mov_b64_e32 v[28:29], 0
	v_mov_b64_e32 v[30:31], 0
	v_mov_b64_e32 v[32:33], 0
	v_mov_b64_e32 v[34:35], 0
	v_mov_b64_e32 v[36:37], 0
	v_mov_b64_e32 v[38:39], 0
	v_mov_b64_e32 v[40:41], 0
	v_mov_b64_e32 v[42:43], 0
	v_mov_b64_e32 v[44:45], 0
	v_mov_b64_e32 v[46:47], 0
	v_mov_b64_e32 v[48:49], 0
	v_mov_b64_e32 v[50:51], 0
	v_mov_b64_e32 v[52:53], 0
	v_mov_b64_e32 v[54:55], 0
	v_mov_b64_e32 v[56:57], 0
	v_mov_b64_e32 v[58:59], 0
	v_mov_b64_e32 v[60:61], 0
	v_mov_b64_e32 v[62:63], 0
	v_mov_b64_e32 v[64:65], 0
	v_mov_b64_e32 v[66:67], 0
	v_mov_b64_e32 v[68:69], 0
	v_mov_b64_e32 v[70:71], 0
	v_mov_b64_e32 v[72:73], 0
	v_mov_b64_e32 v[74:75], 0
	v_mov_b64_e32 v[76:77], 0
	v_mov_b64_e32 v[78:79], 0
	v_mov_b64_e32 v[80:81], 0
	v_mov_b64_e32 v[82:83], 0
	v_mov_b64_e32 v[84:85], 0
	v_mov_b64_e32 v[86:87], 0
	v_mov_b64_e32 v[88:89], 0
	v_mov_b64_e32 v[90:91], 0
	v_mov_b64_e32 v[92:93], 0
	v_mov_b64_e32 v[94:95], 0
	v_mov_b64_e32 v[96:97], 0
	v_mov_b64_e32 v[98:99], 0
	v_mov_b64_e32 v[100:101], 0
	v_mov_b64_e32 v[102:103], 0
	v_mov_b64_e32 v[104:105], 0
	v_mov_b64_e32 v[106:107], 0
	v_mov_b64_e32 v[108:109], 0
	v_mov_b64_e32 v[110:111], 0
	v_mov_b64_e32 v[112:113], 0
	v_mov_b64_e32 v[114:115], 0
	v_mov_b64_e32 v[116:117], 0
	v_mov_b64_e32 v[118:119], 0
	v_mov_b64_e32 v[128:129], 0
	v_mov_b64_e32 v[130:131], 0
	v_mov_b64_e32 v[132:133], 0
	v_mov_b64_e32 v[134:135], 0

.LBB0_990:
	v_cmp_lt_i64_e32 vcc, s[14:15], v[198:199]
	v_readlane_b32 s14, v254, 25
	v_readlane_b32 s15, v254, 26
	s_add_u32 s14, s14, s10
	s_addc_u32 s15, s15, s11
	s_and_b64 s[16:17], vcc, exec
	s_cselect_b32 s0, s15, s21
	s_cselect_b32 s7, s14, s20
	s_add_u32 s16, s27, s12
	s_addc_u32 s17, s28, s13
	s_and_b64 s[24:25], vcc, exec
	s_cselect_b32 s9, s17, s23
	s_cselect_b32 s64, s16, s22
	s_add_u32 s20, s20, 0x40080
	s_addc_u32 s21, s21, 0
	s_add_u32 s65, s22, 0x100
	v_mov_b32_e32 v0, 0
	s_addc_u32 s66, s23, 0
	s_mov_b32 s67, -2
	v_mov_b64_e32 v[0:1], 0
	v_mov_b64_e32 v[2:3], 0
	v_mov_b64_e32 v[4:5], 0
	v_mov_b64_e32 v[6:7], 0
	v_mov_b64_e32 v[8:9], 0
	v_mov_b64_e32 v[10:11], 0
	v_mov_b64_e32 v[12:13], 0
	v_mov_b64_e32 v[14:15], 0
	v_mov_b64_e32 v[16:17], 0
	v_mov_b64_e32 v[18:19], 0
	v_mov_b64_e32 v[20:21], 0
	v_mov_b64_e32 v[22:23], 0
	v_mov_b64_e32 v[24:25], 0
	v_mov_b64_e32 v[26:27], 0
	v_mov_b64_e32 v[28:29], 0
	v_mov_b64_e32 v[30:31], 0
	v_mov_b64_e32 v[32:33], 0
	v_mov_b64_e32 v[34:35], 0
	v_mov_b64_e32 v[36:37], 0
	v_mov_b64_e32 v[38:39], 0
	v_mov_b64_e32 v[40:41], 0
	v_mov_b64_e32 v[42:43], 0
	v_mov_b64_e32 v[44:45], 0
	v_mov_b64_e32 v[46:47], 0
	v_mov_b64_e32 v[48:49], 0
	v_mov_b64_e32 v[50:51], 0
	v_mov_b64_e32 v[52:53], 0
	v_mov_b64_e32 v[54:55], 0
	v_mov_b64_e32 v[56:57], 0
	v_mov_b64_e32 v[58:59], 0
	v_mov_b64_e32 v[60:61], 0
	v_mov_b64_e32 v[62:63], 0
	v_mov_b64_e32 v[64:65], 0
	v_mov_b64_e32 v[66:67], 0
	v_mov_b64_e32 v[76:77], 0
	v_mov_b64_e32 v[78:79], 0
	v_mov_b64_e32 v[80:81], 0
	v_mov_b64_e32 v[82:83], 0
	v_mov_b64_e32 v[84:85], 0
	v_mov_b64_e32 v[86:87], 0
	v_mov_b64_e32 v[88:89], 0
	v_mov_b64_e32 v[90:91], 0
	v_mov_b64_e32 v[92:93], 0
	v_mov_b64_e32 v[94:95], 0
	v_mov_b64_e32 v[96:97], 0
	v_mov_b64_e32 v[98:99], 0
	v_mov_b64_e32 v[100:101], 0
	v_mov_b64_e32 v[102:103], 0
	v_mov_b64_e32 v[104:105], 0
	v_mov_b64_e32 v[106:107], 0
	v_mov_b64_e32 v[108:109], 0
	v_mov_b64_e32 v[110:111], 0
	v_mov_b64_e32 v[112:113], 0
	v_mov_b64_e32 v[114:115], 0
	v_mov_b64_e32 v[116:117], 0
	v_mov_b64_e32 v[118:119], 0
	v_mov_b64_e32 v[120:121], 0
	v_mov_b64_e32 v[122:123], 0
	v_mov_b64_e32 v[124:125], 0
	v_mov_b64_e32 v[126:127], 0
	v_mov_b64_e32 v[128:129], 0
	v_mov_b64_e32 v[130:131], 0
	v_mov_b64_e32 v[132:133], 0
	v_mov_b64_e32 v[134:135], 0

.LBB0_1029:
	v_cmp_lt_i64_e32 vcc, s[14:15], v[204:205]
	s_add_u32 s14, s86, s10
	s_addc_u32 s15, s87, s11
	s_and_b64 s[16:17], vcc, exec
	s_cselect_b32 s7, s15, s21
	s_cselect_b32 s9, s14, s20
	s_add_u32 s16, s27, s12
	s_addc_u32 s17, s28, s13
	s_and_b64 s[24:25], vcc, exec
	s_cselect_b32 s47, s17, s23
	s_cselect_b32 s64, s16, s22
	s_add_u32 s20, s20, 0x40080
	s_addc_u32 s21, s21, 0
	s_add_u32 s65, s22, 0x100
	v_mov_b32_e32 v0, 0
	s_addc_u32 s66, s23, 0
	s_mov_b32 s67, -2
	v_mov_b64_e32 v[0:1], 0
	v_mov_b64_e32 v[2:3], 0
	v_mov_b64_e32 v[4:5], 0
	v_mov_b64_e32 v[6:7], 0
	v_mov_b64_e32 v[8:9], 0
	v_mov_b64_e32 v[10:11], 0
	v_mov_b64_e32 v[12:13], 0
	v_mov_b64_e32 v[14:15], 0
	v_mov_b64_e32 v[16:17], 0
	v_mov_b64_e32 v[18:19], 0
	v_mov_b64_e32 v[20:21], 0
	v_mov_b64_e32 v[22:23], 0
	v_mov_b64_e32 v[24:25], 0
	v_mov_b64_e32 v[26:27], 0
	v_mov_b64_e32 v[28:29], 0
	v_mov_b64_e32 v[30:31], 0
	v_mov_b64_e32 v[32:33], 0
	v_mov_b64_e32 v[34:35], 0
	v_mov_b64_e32 v[36:37], 0
	v_mov_b64_e32 v[38:39], 0
	v_mov_b64_e32 v[40:41], 0
	v_mov_b64_e32 v[42:43], 0
	v_mov_b64_e32 v[44:45], 0
	v_mov_b64_e32 v[46:47], 0
	v_mov_b64_e32 v[48:49], 0
	v_mov_b64_e32 v[50:51], 0
	v_mov_b64_e32 v[52:53], 0
	v_mov_b64_e32 v[54:55], 0
	v_mov_b64_e32 v[56:57], 0
	v_mov_b64_e32 v[58:59], 0
	v_mov_b64_e32 v[60:61], 0
	v_mov_b64_e32 v[62:63], 0
	v_mov_b64_e32 v[64:65], 0
	v_mov_b64_e32 v[66:67], 0
	v_mov_b64_e32 v[68:69], 0
	v_mov_b64_e32 v[70:71], 0
	v_mov_b64_e32 v[72:73], 0
	v_mov_b64_e32 v[74:75], 0
	v_mov_b64_e32 v[76:77], 0
	v_mov_b64_e32 v[78:79], 0
	v_mov_b64_e32 v[80:81], 0
	v_mov_b64_e32 v[82:83], 0
	v_mov_b64_e32 v[84:85], 0
	v_mov_b64_e32 v[86:87], 0
	v_mov_b64_e32 v[88:89], 0
	v_mov_b64_e32 v[90:91], 0
	v_mov_b64_e32 v[92:93], 0
	v_mov_b64_e32 v[94:95], 0
	v_mov_b64_e32 v[96:97], 0
	v_mov_b64_e32 v[98:99], 0
	v_mov_b64_e32 v[100:101], 0
	v_mov_b64_e32 v[102:103], 0
	v_mov_b64_e32 v[104:105], 0
	v_mov_b64_e32 v[106:107], 0
	v_mov_b64_e32 v[108:109], 0
	v_mov_b64_e32 v[110:111], 0
	v_mov_b64_e32 v[112:113], 0
	v_mov_b64_e32 v[114:115], 0
	v_mov_b64_e32 v[116:117], 0
	v_mov_b64_e32 v[118:119], 0
	v_mov_b64_e32 v[120:121], 0
	v_mov_b64_e32 v[122:123], 0
	v_mov_b64_e32 v[124:125], 0
	v_mov_b64_e32 v[126:127], 0
.LBB0_1030:
	v_or_b32_e32 v140, 0x10000, v144
	v_add_u32_e32 v141, 0x10400, v144
	ds_read_b128 v[146:149], v140
	ds_read_b128 v[150:153], v141
	v_add_u32_e32 v140, 0x10800, v144
	v_add_u32_e32 v141, 0x10c00, v144
	ds_read_b128 v[154:157], v140
	ds_read_b128 v[158:161], v141
	s_add_u32 s22, s20, 0xfffc0080
	s_addc_u32 s23, s21, -1
	s_cmp_eq_u32 s67, 12
	s_cselect_b32 s25, s7, s23
	s_cselect_b32 s24, s9, s22
	s_cselect_b32 s23, s47, s66
	s_cselect_b32 s22, s64, s65
	v_lshl_add_u64 v[140:141], s[20:21], 0, v[136:137]
	s_add_i32 m0, s29, 0xc000
	ds_read_b128 v[162:165], v143
	ds_read_b128 v[166:169], v143 offset:1024
	ds_read_b128 v[170:173], v143 offset:2048
	ds_read_b128 v[174:177], v143 offset:3072
	ds_read_b128 v[178:181], v143 offset:4096
	ds_read_b128 v[182:185], v143 offset:5120
	ds_read_b128 v[186:189], v143 offset:6144
	ds_read_b128 v[206:209], v143 offset:7168
	global_load_lds_dwordx4 v[140:141], off
	v_lshl_add_u64 v[140:141], s[20:21], 0, v[138:139]
	s_add_i32 m0, s29, 0xe000
	s_nop 0
	global_load_lds_dwordx4 v[140:141], off
	s_waitcnt lgkmcnt(8)
	s_barrier
	s_waitcnt lgkmcnt(0)
	s_setprio 1
	s_waitcnt lgkmcnt(0)
	v_mfma_f32_16x16x32_bf16 v[124:127], v[146:149], v[162:165], v[124:127]
	v_mfma_f32_16x16x32_bf16 v[120:123], v[154:157], v[162:165], v[120:123]
	v_mfma_f32_16x16x32_bf16 v[108:111], v[146:149], v[170:173], v[108:111]
	v_mfma_f32_16x16x32_bf16 v[104:107], v[154:157], v[170:173], v[104:107]
	v_mfma_f32_16x16x32_bf16 v[92:95], v[146:149], v[178:181], v[92:95]
	v_mfma_f32_16x16x32_bf16 v[88:91], v[154:157], v[178:181], v[88:91]
	v_mfma_f32_16x16x32_bf16 v[76:79], v[146:149], v[186:189], v[76:79]
	v_mfma_f32_16x16x32_bf16 v[72:75], v[154:157], v[186:189], v[72:75]
	v_mfma_f32_16x16x32_bf16 v[124:127], v[150:153], v[166:169], v[124:127]
	v_mfma_f32_16x16x32_bf16 v[120:123], v[158:161], v[166:169], v[120:123]
	v_mfma_f32_16x16x32_bf16 v[108:111], v[150:153], v[174:177], v[108:111]
	v_mfma_f32_16x16x32_bf16 v[104:107], v[158:161], v[174:177], v[104:107]
	v_mfma_f32_16x16x32_bf16 v[92:95], v[150:153], v[182:185], v[92:95]
	v_mfma_f32_16x16x32_bf16 v[88:91], v[158:161], v[182:185], v[88:91]
	v_mfma_f32_16x16x32_bf16 v[76:79], v[150:153], v[206:209], v[76:79]
	v_mfma_f32_16x16x32_bf16 v[72:75], v[158:161], v[206:209], v[72:75]
	s_setprio 0
	s_barrier
	v_or_b32_e32 v140, 0x14000, v144
	v_add_u32_e32 v141, 0x14400, v144
	ds_read_b128 v[210:213], v140
	ds_read_b128 v[214:217], v141
	v_add_u32_e32 v140, 0x14800, v144
	v_add_u32_e32 v141, 0x14c00, v144
	s_mov_b32 m0, s19
	ds_read_b128 v[244:247], v140
	ds_read_b128 v[248:251], v141
	v_lshl_add_u64 v[140:141], s[22:23], 0, v[132:133]
	global_load_lds_dwordx4 v[140:141], off
	v_lshl_add_u64 v[190:191], s[22:23], 0, v[128:129]
	s_mov_b32 m0, s31
	s_nop 0
	global_load_lds_dwordx4 v[190:191], off
	s_barrier
	s_waitcnt lgkmcnt(0)
	s_setprio 1
	s_waitcnt lgkmcnt(0)
	v_mfma_f32_16x16x32_bf16 v[116:119], v[210:213], v[162:165], v[116:119]
	v_mfma_f32_16x16x32_bf16 v[112:115], v[244:247], v[162:165], v[112:115]
	v_mfma_f32_16x16x32_bf16 v[100:103], v[210:213], v[170:173], v[100:103]
	v_mfma_f32_16x16x32_bf16 v[96:99], v[244:247], v[170:173], v[96:99]
	v_mfma_f32_16x16x32_bf16 v[84:87], v[210:213], v[178:181], v[84:87]
	v_mfma_f32_16x16x32_bf16 v[80:83], v[244:247], v[178:181], v[80:83]
	v_mfma_f32_16x16x32_bf16 v[68:71], v[210:213], v[186:189], v[68:71]
	v_mfma_f32_16x16x32_bf16 v[64:67], v[244:247], v[186:189], v[64:67]
	v_mfma_f32_16x16x32_bf16 v[116:119], v[214:217], v[166:169], v[116:119]
	v_mfma_f32_16x16x32_bf16 v[112:115], v[248:251], v[166:169], v[112:115]
	v_mfma_f32_16x16x32_bf16 v[100:103], v[214:217], v[174:177], v[100:103]
	v_mfma_f32_16x16x32_bf16 v[96:99], v[248:251], v[174:177], v[96:99]
	v_mfma_f32_16x16x32_bf16 v[84:87], v[214:217], v[182:185], v[84:87]
	v_mfma_f32_16x16x32_bf16 v[80:83], v[248:251], v[182:185], v[80:83]
	v_mfma_f32_16x16x32_bf16 v[68:71], v[214:217], v[206:209], v[68:71]
	v_mfma_f32_16x16x32_bf16 v[64:67], v[248:251], v[206:209], v[64:67]
	s_setprio 0
	s_mov_b32 m0, s29
	v_lshl_add_u64 v[218:219], s[24:25], 0, v[134:135]
	s_barrier
	ds_read_b128 v[162:165], v143 offset:16384
	ds_read_b128 v[166:169], v143 offset:17408
	ds_read_b128 v[170:173], v143 offset:18432
	ds_read_b128 v[174:177], v143 offset:19456
	ds_read_b128 v[178:181], v143 offset:20480
	ds_read_b128 v[182:185], v143 offset:21504
	ds_read_b128 v[186:189], v143 offset:22528
	ds_read_b128 v[206:209], v143 offset:23552
	global_load_lds_dwordx4 v[218:219], off
	v_lshl_add_u64 v[228:229], s[24:25], 0, v[130:131]
	s_mov_b32 m0, s34
	s_nop 0
	global_load_lds_dwordx4 v[228:229], off
	s_barrier
	s_waitcnt lgkmcnt(0)
	s_setprio 1
	s_waitcnt lgkmcnt(0)
	v_mfma_f32_16x16x32_bf16 v[60:63], v[146:149], v[162:165], v[60:63]
	v_mfma_f32_16x16x32_bf16 v[56:59], v[154:157], v[162:165], v[56:59]
	v_mfma_f32_16x16x32_bf16 v[44:47], v[146:149], v[170:173], v[44:47]
	v_mfma_f32_16x16x32_bf16 v[40:43], v[154:157], v[170:173], v[40:43]
	v_mfma_f32_16x16x32_bf16 v[28:31], v[146:149], v[178:181], v[28:31]
	v_mfma_f32_16x16x32_bf16 v[24:27], v[154:157], v[178:181], v[24:27]
	v_mfma_f32_16x16x32_bf16 v[12:15], v[146:149], v[186:189], v[12:15]
	v_mfma_f32_16x16x32_bf16 v[8:11], v[154:157], v[186:189], v[8:11]
	v_mfma_f32_16x16x32_bf16 v[60:63], v[150:153], v[166:169], v[60:63]
	v_mfma_f32_16x16x32_bf16 v[56:59], v[158:161], v[166:169], v[56:59]
	v_mfma_f32_16x16x32_bf16 v[44:47], v[150:153], v[174:177], v[44:47]
	v_mfma_f32_16x16x32_bf16 v[40:43], v[158:161], v[174:177], v[40:43]
	v_mfma_f32_16x16x32_bf16 v[28:31], v[150:153], v[182:185], v[28:31]
	v_mfma_f32_16x16x32_bf16 v[24:27], v[158:161], v[182:185], v[24:27]
	v_mfma_f32_16x16x32_bf16 v[12:15], v[150:153], v[206:209], v[12:15]
	v_mfma_f32_16x16x32_bf16 v[8:11], v[158:161], v[206:209], v[8:11]
	s_setprio 0
	s_barrier
	s_add_u32 s68, s22, 0x40000
	s_addc_u32 s69, s23, 0
	s_mov_b32 m0, s35
	v_lshl_add_u64 v[146:147], s[68:69], 0, v[132:133]
	global_load_lds_dwordx4 v[146:147], off
	v_lshl_add_u64 v[146:147], s[68:69], 0, v[128:129]
	s_mov_b32 m0, s36
	s_nop 0
	global_load_lds_dwordx4 v[146:147], off
	s_waitcnt vmcnt(6)
	s_barrier
	s_setprio 1
	v_mfma_f32_16x16x32_bf16 v[52:55], v[210:213], v[162:165], v[52:55]
	v_mfma_f32_16x16x32_bf16 v[48:51], v[244:247], v[162:165], v[48:51]
	v_mfma_f32_16x16x32_bf16 v[36:39], v[210:213], v[170:173], v[36:39]
	v_mfma_f32_16x16x32_bf16 v[32:35], v[244:247], v[170:173], v[32:35]
	v_mfma_f32_16x16x32_bf16 v[20:23], v[210:213], v[178:181], v[20:23]
	v_mfma_f32_16x16x32_bf16 v[16:19], v[244:247], v[178:181], v[16:19]
	v_mfma_f32_16x16x32_bf16 v[4:7], v[210:213], v[186:189], v[4:7]
	v_mfma_f32_16x16x32_bf16 v[0:3], v[244:247], v[186:189], v[0:3]
	v_mfma_f32_16x16x32_bf16 v[52:55], v[214:217], v[166:169], v[52:55]
	v_mfma_f32_16x16x32_bf16 v[48:51], v[248:251], v[166:169], v[48:51]
	v_mfma_f32_16x16x32_bf16 v[36:39], v[214:217], v[174:177], v[36:39]
	v_mfma_f32_16x16x32_bf16 v[32:35], v[248:251], v[174:177], v[32:35]
	v_mfma_f32_16x16x32_bf16 v[20:23], v[214:217], v[182:185], v[20:23]
	v_mfma_f32_16x16x32_bf16 v[16:19], v[248:251], v[182:185], v[16:19]
	v_mfma_f32_16x16x32_bf16 v[4:7], v[214:217], v[206:209], v[4:7]
	v_mfma_f32_16x16x32_bf16 v[0:3], v[248:251], v[206:209], v[0:3]
	s_setprio 0
	v_or_b32_e32 v145, 0x18000, v144
	v_add_u32_e32 v150, 0x18400, v144
	s_barrier
	ds_read_b128 v[146:149], v145
	ds_read_b128 v[150:153], v150
	v_add_u32_e32 v145, 0x18800, v144
	v_add_u32_e32 v158, 0x18c00, v144
	ds_read_b128 v[154:157], v145
	ds_read_b128 v[158:161], v158
	s_add_u32 s24, s24, 0x40000
	s_addc_u32 s25, s25, 0
	s_mov_b32 m0, s37
	v_lshl_add_u64 v[210:211], s[24:25], 0, v[134:135]
	ds_read_b128 v[162:165], v143 offset:32768
	ds_read_b128 v[166:169], v143 offset:33792
	ds_read_b128 v[170:173], v143 offset:34816
	ds_read_b128 v[174:177], v143 offset:35840
	ds_read_b128 v[178:181], v143 offset:36864
	ds_read_b128 v[182:185], v143 offset:37888
	ds_read_b128 v[186:189], v143 offset:38912
	ds_read_b128 v[206:209], v143 offset:39936
	global_load_lds_dwordx4 v[210:211], off
	v_lshl_add_u64 v[210:211], s[24:25], 0, v[130:131]
	s_mov_b32 m0, s38
	s_nop 0
	global_load_lds_dwordx4 v[210:211], off
	s_waitcnt lgkmcnt(8)
	s_barrier
	s_waitcnt lgkmcnt(0)
	s_setprio 1
	s_waitcnt lgkmcnt(0)
	v_mfma_f32_16x16x32_bf16 v[124:127], v[146:149], v[162:165], v[124:127]
	v_mfma_f32_16x16x32_bf16 v[120:123], v[154:157], v[162:165], v[120:123]
	v_mfma_f32_16x16x32_bf16 v[108:111], v[146:149], v[170:173], v[108:111]
	v_mfma_f32_16x16x32_bf16 v[104:107], v[154:157], v[170:173], v[104:107]
	v_mfma_f32_16x16x32_bf16 v[92:95], v[146:149], v[178:181], v[92:95]
	v_mfma_f32_16x16x32_bf16 v[88:91], v[154:157], v[178:181], v[88:91]
	v_mfma_f32_16x16x32_bf16 v[76:79], v[146:149], v[186:189], v[76:79]
	v_mfma_f32_16x16x32_bf16 v[72:75], v[154:157], v[186:189], v[72:75]
	v_mfma_f32_16x16x32_bf16 v[124:127], v[150:153], v[166:169], v[124:127]
	v_mfma_f32_16x16x32_bf16 v[120:123], v[158:161], v[166:169], v[120:123]
	v_mfma_f32_16x16x32_bf16 v[108:111], v[150:153], v[174:177], v[108:111]
	v_mfma_f32_16x16x32_bf16 v[104:107], v[158:161], v[174:177], v[104:107]
	v_mfma_f32_16x16x32_bf16 v[92:95], v[150:153], v[182:185], v[92:95]
	v_mfma_f32_16x16x32_bf16 v[88:91], v[158:161], v[182:185], v[88:91]
	v_mfma_f32_16x16x32_bf16 v[76:79], v[150:153], v[206:209], v[76:79]
	v_mfma_f32_16x16x32_bf16 v[72:75], v[158:161], v[206:209], v[72:75]
	s_setprio 0
	s_barrier
	v_or_b32_e32 v145, 0x1c000, v144
	s_mov_b32 m0, s39
	v_add_u32_e32 v201, 0x1c400, v144
	ds_read_b128 v[210:213], v145
	ds_read_b128 v[214:217], v201
	v_add_u32_e32 v145, 0x1c800, v144
	v_lshl_add_u64 v[140:141], v[140:141], 0, s[94:95]
	v_add_u32_e32 v201, 0x1cc00, v144
	ds_read_b128 v[244:247], v145
	ds_read_b128 v[248:251], v201
	global_load_lds_dwordx4 v[140:141], off
	v_lshl_add_u64 v[140:141], v[190:191], 0, s[94:95]
	s_mov_b32 m0, s40
	s_nop 0
	global_load_lds_dwordx4 v[140:141], off
	s_barrier
	s_waitcnt lgkmcnt(0)
	s_setprio 1
	s_waitcnt lgkmcnt(0)
	v_mfma_f32_16x16x32_bf16 v[116:119], v[210:213], v[162:165], v[116:119]
	v_mfma_f32_16x16x32_bf16 v[112:115], v[244:247], v[162:165], v[112:115]
	v_mfma_f32_16x16x32_bf16 v[100:103], v[210:213], v[170:173], v[100:103]
	v_mfma_f32_16x16x32_bf16 v[96:99], v[244:247], v[170:173], v[96:99]
	v_mfma_f32_16x16x32_bf16 v[84:87], v[210:213], v[178:181], v[84:87]
	v_mfma_f32_16x16x32_bf16 v[80:83], v[244:247], v[178:181], v[80:83]
	v_mfma_f32_16x16x32_bf16 v[68:71], v[210:213], v[186:189], v[68:71]
	v_mfma_f32_16x16x32_bf16 v[64:67], v[244:247], v[186:189], v[64:67]
	v_mfma_f32_16x16x32_bf16 v[116:119], v[214:217], v[166:169], v[116:119]
	v_mfma_f32_16x16x32_bf16 v[112:115], v[248:251], v[166:169], v[112:115]
	v_mfma_f32_16x16x32_bf16 v[100:103], v[214:217], v[174:177], v[100:103]
	v_mfma_f32_16x16x32_bf16 v[96:99], v[248:251], v[174:177], v[96:99]
	v_mfma_f32_16x16x32_bf16 v[84:87], v[214:217], v[182:185], v[84:87]
	v_mfma_f32_16x16x32_bf16 v[80:83], v[248:251], v[182:185], v[80:83]
	v_mfma_f32_16x16x32_bf16 v[68:71], v[214:217], v[206:209], v[68:71]
	v_mfma_f32_16x16x32_bf16 v[64:67], v[248:251], v[206:209], v[64:67]
	s_setprio 0
	s_mov_b32 m0, s41
	v_lshl_add_u64 v[140:141], v[218:219], 0, s[94:95]
	s_barrier
	ds_read_b128 v[162:165], v143 offset:49152
	ds_read_b128 v[166:169], v143 offset:50176
	ds_read_b128 v[170:173], v143 offset:51200
	ds_read_b128 v[174:177], v143 offset:52224
	ds_read_b128 v[178:181], v143 offset:53248
	ds_read_b128 v[182:185], v143 offset:54272
	ds_read_b128 v[186:189], v143 offset:55296
	ds_read_b128 v[206:209], v143 offset:56320
	global_load_lds_dwordx4 v[140:141], off
	v_lshl_add_u64 v[140:141], v[228:229], 0, s[94:95]
	s_mov_b32 m0, s42
	s_nop 0
	global_load_lds_dwordx4 v[140:141], off
	s_barrier
	s_waitcnt lgkmcnt(0)
	s_setprio 1
	s_waitcnt lgkmcnt(0)
	v_mfma_f32_16x16x32_bf16 v[60:63], v[146:149], v[162:165], v[60:63]
	v_mfma_f32_16x16x32_bf16 v[56:59], v[154:157], v[162:165], v[56:59]
	v_mfma_f32_16x16x32_bf16 v[44:47], v[146:149], v[170:173], v[44:47]
	v_mfma_f32_16x16x32_bf16 v[40:43], v[154:157], v[170:173], v[40:43]
	v_mfma_f32_16x16x32_bf16 v[28:31], v[146:149], v[178:181], v[28:31]
	v_mfma_f32_16x16x32_bf16 v[24:27], v[154:157], v[178:181], v[24:27]
	v_mfma_f32_16x16x32_bf16 v[12:15], v[146:149], v[186:189], v[12:15]
	v_mfma_f32_16x16x32_bf16 v[8:11], v[154:157], v[186:189], v[8:11]
	v_mfma_f32_16x16x32_bf16 v[60:63], v[150:153], v[166:169], v[60:63]
	v_mfma_f32_16x16x32_bf16 v[56:59], v[158:161], v[166:169], v[56:59]
	v_mfma_f32_16x16x32_bf16 v[44:47], v[150:153], v[174:177], v[44:47]
	v_mfma_f32_16x16x32_bf16 v[40:43], v[158:161], v[174:177], v[40:43]
	v_mfma_f32_16x16x32_bf16 v[28:31], v[150:153], v[182:185], v[28:31]
	v_mfma_f32_16x16x32_bf16 v[24:27], v[158:161], v[182:185], v[24:27]
	v_mfma_f32_16x16x32_bf16 v[12:15], v[150:153], v[206:209], v[12:15]
	v_mfma_f32_16x16x32_bf16 v[8:11], v[158:161], v[206:209], v[8:11]
	s_setprio 0
	s_barrier
	s_add_u32 s22, s22, 0x40080
	s_addc_u32 s23, s23, 0
	s_mov_b32 m0, s43
	v_lshl_add_u64 v[140:141], s[22:23], 0, v[132:133]
	global_load_lds_dwordx4 v[140:141], off
	v_lshl_add_u64 v[140:141], s[22:23], 0, v[128:129]
	s_mov_b32 m0, s44
	s_nop 0
	global_load_lds_dwordx4 v[140:141], off
	s_waitcnt vmcnt(6)
	s_barrier
	s_setprio 1
	v_mfma_f32_16x16x32_bf16 v[52:55], v[210:213], v[162:165], v[52:55]
	v_mfma_f32_16x16x32_bf16 v[48:51], v[244:247], v[162:165], v[48:51]
	v_mfma_f32_16x16x32_bf16 v[36:39], v[210:213], v[170:173], v[36:39]
	v_mfma_f32_16x16x32_bf16 v[32:35], v[244:247], v[170:173], v[32:35]
	v_mfma_f32_16x16x32_bf16 v[20:23], v[210:213], v[178:181], v[20:23]
	v_mfma_f32_16x16x32_bf16 v[16:19], v[244:247], v[178:181], v[16:19]
	v_mfma_f32_16x16x32_bf16 v[4:7], v[210:213], v[186:189], v[4:7]
	v_mfma_f32_16x16x32_bf16 v[0:3], v[244:247], v[186:189], v[0:3]
	v_mfma_f32_16x16x32_bf16 v[52:55], v[214:217], v[166:169], v[52:55]
	v_mfma_f32_16x16x32_bf16 v[48:51], v[248:251], v[166:169], v[48:51]
	v_mfma_f32_16x16x32_bf16 v[36:39], v[214:217], v[174:177], v[36:39]
	v_mfma_f32_16x16x32_bf16 v[32:35], v[248:251], v[174:177], v[32:35]
	v_mfma_f32_16x16x32_bf16 v[20:23], v[214:217], v[182:185], v[20:23]
	v_mfma_f32_16x16x32_bf16 v[16:19], v[248:251], v[182:185], v[16:19]
	v_mfma_f32_16x16x32_bf16 v[4:7], v[214:217], v[206:209], v[4:7]
	v_mfma_f32_16x16x32_bf16 v[0:3], v[248:251], v[206:209], v[0:3]
	s_setprio 0
	s_add_i32 s67, s67, 2
	s_add_u32 s20, s20, 0x100
	s_addc_u32 s21, s21, 0
	s_add_u32 s65, s65, 0x100
	s_addc_u32 s66, s66, 0
	s_cmp_gt_u32 s67, 13
	s_barrier
	s_cbranch_scc0 .LBB0_1030
	v_lshl_add_u32 v140, s18, 8, v142
	v_ashrrev_i32_e32 v141, 31, v140
	v_readlane_b32 s20, v254, 15
	v_lshlrev_b64 v[140:141], 13, v[140:141]
	v_readlane_b32 s21, v254, 16
	v_max_f32_e32 v146, 0, v120
	v_lshl_add_u64 v[140:141], s[20:21], 0, v[140:141]
	s_lshl_b32 s20, s46, 8
	v_max_f32_e32 v147, 0, v121
	s_ashr_i32 s21, s20, 31
	v_max_f32_e32 v124, 0, v124
	v_max_f32_e32 v125, 0, v125
	v_max_f32_e32 v126, 0, v126
	v_max_f32_e32 v127, 0, v127
	v_max_f32_e32 v148, 0, v122
	v_lshl_add_u64 v[140:141], s[20:21], 1, v[140:141]
	v_max_f32_e32 v149, 0, v123
	v_pk_mul_f32 v[120:121], v[124:125], v[124:125]
	v_pk_mul_f32 v[122:123], v[126:127], v[126:127]
	v_lshl_add_u64 v[140:141], v[140:141], 0, s[0:1]
	v_cvt_pk_bf16_f32 v120, v120, v121
	v_cvt_pk_bf16_f32 v121, v122, v123
	v_pk_mul_f32 v[122:123], v[146:147], v[146:147]
	v_pk_mul_f32 v[124:125], v[148:149], v[148:149]
	v_lshl_add_u64 v[140:141], v[140:141], 0, v[192:193]
	v_cvt_pk_bf16_f32 v122, v122, v123
	v_cvt_pk_bf16_f32 v123, v124, v125
	global_store_dwordx4 v[140:141], v[120:123], off
	s_nop 1
	v_max_f32_e32 v120, 0, v112
	v_max_f32_e32 v121, 0, v113
	v_max_f32_e32 v116, 0, v116
	v_max_f32_e32 v117, 0, v117
	v_max_f32_e32 v118, 0, v118
	v_max_f32_e32 v119, 0, v119
	v_max_f32_e32 v122, 0, v114
	v_max_f32_e32 v123, 0, v115
	v_pk_mul_f32 v[112:113], v[116:117], v[116:117]
	v_pk_mul_f32 v[114:115], v[118:119], v[118:119]
	v_cvt_pk_bf16_f32 v112, v112, v113
	v_cvt_pk_bf16_f32 v113, v114, v115
	v_pk_mul_f32 v[114:115], v[120:121], v[120:121]
	v_pk_mul_f32 v[116:117], v[122:123], v[122:123]
	v_cvt_pk_bf16_f32 v114, v114, v115
	v_cvt_pk_bf16_f32 v115, v116, v117
	global_store_dwordx4 v[140:141], v[112:115], off offset:256
	s_nop 1
	v_max_f32_e32 v112, 0, v104
	v_max_f32_e32 v113, 0, v105
	v_max_f32_e32 v108, 0, v108
	v_max_f32_e32 v109, 0, v109
	v_max_f32_e32 v110, 0, v110
	v_max_f32_e32 v111, 0, v111
	v_max_f32_e32 v114, 0, v106
	v_max_f32_e32 v115, 0, v107
	v_pk_mul_f32 v[104:105], v[108:109], v[108:109]
	v_pk_mul_f32 v[106:107], v[110:111], v[110:111]
	v_cvt_pk_bf16_f32 v104, v104, v105
	v_cvt_pk_bf16_f32 v105, v106, v107
	v_pk_mul_f32 v[106:107], v[112:113], v[112:113]
	v_pk_mul_f32 v[108:109], v[114:115], v[114:115]
	s_mov_b32 s7, 0x20000
	v_cvt_pk_bf16_f32 v106, v106, v107
	v_cvt_pk_bf16_f32 v107, v108, v109
	v_add_co_u32_e32 v108, vcc, s7, v140
	s_nop 0
	v_addc_co_u32_e32 v109, vcc, 0, v141, vcc
	global_store_dwordx4 v[108:109], v[104:107], off
	s_nop 1
	v_max_f32_e32 v104, 0, v96
	v_max_f32_e32 v105, 0, v97
	v_max_f32_e32 v100, 0, v100
	v_max_f32_e32 v101, 0, v101
	v_max_f32_e32 v102, 0, v102
	v_max_f32_e32 v103, 0, v103
	v_max_f32_e32 v106, 0, v98
	v_max_f32_e32 v107, 0, v99
	v_pk_mul_f32 v[96:97], v[100:101], v[100:101]
	v_pk_mul_f32 v[98:99], v[102:103], v[102:103]
	v_cvt_pk_bf16_f32 v96, v96, v97
	v_cvt_pk_bf16_f32 v97, v98, v99
	v_pk_mul_f32 v[98:99], v[104:105], v[104:105]
	v_pk_mul_f32 v[100:101], v[106:107], v[106:107]
	v_cvt_pk_bf16_f32 v98, v98, v99
	v_cvt_pk_bf16_f32 v99, v100, v101
	global_store_dwordx4 v[108:109], v[96:99], off offset:256
	s_nop 1
	v_max_f32_e32 v96, 0, v88
	v_max_f32_e32 v97, 0, v89
	v_max_f32_e32 v92, 0, v92
	v_max_f32_e32 v93, 0, v93
	v_max_f32_e32 v94, 0, v94
	v_max_f32_e32 v95, 0, v95
	v_max_f32_e32 v98, 0, v90
	v_max_f32_e32 v99, 0, v91
	v_pk_mul_f32 v[88:89], v[92:93], v[92:93]
	v_pk_mul_f32 v[90:91], v[94:95], v[94:95]
	v_cvt_pk_bf16_f32 v88, v88, v89
	v_cvt_pk_bf16_f32 v89, v90, v91
	v_pk_mul_f32 v[90:91], v[96:97], v[96:97]
	v_pk_mul_f32 v[92:93], v[98:99], v[98:99]
	s_mov_b32 s7, 0x40000
	v_cvt_pk_bf16_f32 v90, v90, v91
	v_cvt_pk_bf16_f32 v91, v92, v93
	v_add_co_u32_e32 v92, vcc, s7, v140
	s_nop 0
	v_addc_co_u32_e32 v93, vcc, 0, v141, vcc
	global_store_dwordx4 v[92:93], v[88:91], off
	s_nop 1
	v_max_f32_e32 v88, 0, v80
	v_max_f32_e32 v89, 0, v81
	v_max_f32_e32 v84, 0, v84
	v_max_f32_e32 v85, 0, v85
	v_max_f32_e32 v86, 0, v86
	v_max_f32_e32 v87, 0, v87
	v_max_f32_e32 v90, 0, v82
	v_max_f32_e32 v91, 0, v83
	v_pk_mul_f32 v[80:81], v[84:85], v[84:85]
	v_pk_mul_f32 v[82:83], v[86:87], v[86:87]
	v_cvt_pk_bf16_f32 v80, v80, v81
	v_cvt_pk_bf16_f32 v81, v82, v83
	v_pk_mul_f32 v[82:83], v[88:89], v[88:89]
	v_pk_mul_f32 v[84:85], v[90:91], v[90:91]
	v_cvt_pk_bf16_f32 v82, v82, v83
	v_cvt_pk_bf16_f32 v83, v84, v85
	global_store_dwordx4 v[92:93], v[80:83], off offset:256
	s_nop 1
	v_max_f32_e32 v80, 0, v72
	v_max_f32_e32 v81, 0, v73
	v_max_f32_e32 v76, 0, v76
	v_max_f32_e32 v77, 0, v77
	v_max_f32_e32 v78, 0, v78
	v_max_f32_e32 v79, 0, v79
	v_max_f32_e32 v82, 0, v74
	v_max_f32_e32 v83, 0, v75
	v_pk_mul_f32 v[72:73], v[76:77], v[76:77]
	v_pk_mul_f32 v[74:75], v[78:79], v[78:79]
	v_cvt_pk_bf16_f32 v72, v72, v73
	v_cvt_pk_bf16_f32 v73, v74, v75
	v_pk_mul_f32 v[74:75], v[80:81], v[80:81]
	v_pk_mul_f32 v[76:77], v[82:83], v[82:83]
	s_mov_b32 s7, 0x60000
	v_cvt_pk_bf16_f32 v74, v74, v75
	v_cvt_pk_bf16_f32 v75, v76, v77
	v_add_co_u32_e32 v76, vcc, s7, v140
	s_nop 0
	v_addc_co_u32_e32 v77, vcc, 0, v141, vcc
	global_store_dwordx4 v[76:77], v[72:75], off
	s_nop 1
	v_max_f32_e32 v72, 0, v64
	v_max_f32_e32 v73, 0, v65
	v_max_f32_e32 v68, 0, v68
	v_max_f32_e32 v69, 0, v69
	v_max_f32_e32 v70, 0, v70
	v_max_f32_e32 v71, 0, v71
	v_max_f32_e32 v74, 0, v66
	v_max_f32_e32 v75, 0, v67
	v_pk_mul_f32 v[64:65], v[68:69], v[68:69]
	v_pk_mul_f32 v[66:67], v[70:71], v[70:71]
	v_cvt_pk_bf16_f32 v64, v64, v65
	v_cvt_pk_bf16_f32 v65, v66, v67
	v_pk_mul_f32 v[66:67], v[72:73], v[72:73]
	v_pk_mul_f32 v[68:69], v[74:75], v[74:75]
	v_cvt_pk_bf16_f32 v66, v66, v67
	v_cvt_pk_bf16_f32 v67, v68, v69
	global_store_dwordx4 v[76:77], v[64:67], off offset:256
	s_nop 1
	v_max_f32_e32 v64, 0, v56
	v_max_f32_e32 v65, 0, v57
	v_max_f32_e32 v60, 0, v60
	v_max_f32_e32 v61, 0, v61
	v_max_f32_e32 v62, 0, v62
	v_max_f32_e32 v63, 0, v63
	v_max_f32_e32 v66, 0, v58
	v_max_f32_e32 v67, 0, v59
	v_pk_mul_f32 v[56:57], v[60:61], v[60:61]
	v_pk_mul_f32 v[58:59], v[62:63], v[62:63]
	v_cvt_pk_bf16_f32 v56, v56, v57
	v_cvt_pk_bf16_f32 v57, v58, v59
	v_pk_mul_f32 v[58:59], v[64:65], v[64:65]
	v_pk_mul_f32 v[60:61], v[66:67], v[66:67]
	s_mov_b32 s7, 0x100000
	v_cvt_pk_bf16_f32 v58, v58, v59
	v_cvt_pk_bf16_f32 v59, v60, v61
	v_add_co_u32_e32 v60, vcc, s7, v140
	s_nop 0
	v_addc_co_u32_e32 v61, vcc, 0, v141, vcc
	global_store_dwordx4 v[60:61], v[56:59], off
	s_nop 1
	v_max_f32_e32 v56, 0, v48
	v_max_f32_e32 v57, 0, v49
	v_max_f32_e32 v52, 0, v52
	v_max_f32_e32 v53, 0, v53
	v_max_f32_e32 v54, 0, v54
	v_max_f32_e32 v55, 0, v55
	v_max_f32_e32 v58, 0, v50
	v_max_f32_e32 v59, 0, v51
	v_pk_mul_f32 v[48:49], v[52:53], v[52:53]
	v_pk_mul_f32 v[50:51], v[54:55], v[54:55]
	v_cvt_pk_bf16_f32 v48, v48, v49
	v_cvt_pk_bf16_f32 v49, v50, v51
	v_pk_mul_f32 v[50:51], v[56:57], v[56:57]
	v_pk_mul_f32 v[52:53], v[58:59], v[58:59]
	v_cvt_pk_bf16_f32 v50, v50, v51
	v_cvt_pk_bf16_f32 v51, v52, v53
	global_store_dwordx4 v[60:61], v[48:51], off offset:256
	s_nop 1
	v_max_f32_e32 v48, 0, v40
	v_max_f32_e32 v49, 0, v41
	v_max_f32_e32 v44, 0, v44
	v_max_f32_e32 v45, 0, v45
	v_max_f32_e32 v46, 0, v46
	v_max_f32_e32 v47, 0, v47
	v_max_f32_e32 v50, 0, v42
	v_max_f32_e32 v51, 0, v43
	v_pk_mul_f32 v[40:41], v[44:45], v[44:45]
	v_pk_mul_f32 v[42:43], v[46:47], v[46:47]
	v_cvt_pk_bf16_f32 v40, v40, v41
	v_cvt_pk_bf16_f32 v41, v42, v43
	v_pk_mul_f32 v[42:43], v[48:49], v[48:49]
	v_pk_mul_f32 v[44:45], v[50:51], v[50:51]
	s_mov_b32 s7, 0x120000
	v_cvt_pk_bf16_f32 v42, v42, v43
	v_cvt_pk_bf16_f32 v43, v44, v45
	v_add_co_u32_e32 v44, vcc, s7, v140
	s_nop 0
	v_addc_co_u32_e32 v45, vcc, 0, v141, vcc
	global_store_dwordx4 v[44:45], v[40:43], off
	s_nop 1
	v_max_f32_e32 v40, 0, v32
	v_max_f32_e32 v41, 0, v33
	v_max_f32_e32 v36, 0, v36
	v_max_f32_e32 v37, 0, v37
	v_max_f32_e32 v38, 0, v38
	v_max_f32_e32 v39, 0, v39
	v_max_f32_e32 v42, 0, v34
	v_max_f32_e32 v43, 0, v35
	v_pk_mul_f32 v[32:33], v[36:37], v[36:37]
	v_pk_mul_f32 v[34:35], v[38:39], v[38:39]
	v_cvt_pk_bf16_f32 v32, v32, v33
	v_cvt_pk_bf16_f32 v33, v34, v35
	v_pk_mul_f32 v[34:35], v[40:41], v[40:41]
	v_pk_mul_f32 v[36:37], v[42:43], v[42:43]
	v_cvt_pk_bf16_f32 v34, v34, v35
	v_cvt_pk_bf16_f32 v35, v36, v37
	global_store_dwordx4 v[44:45], v[32:35], off offset:256
	s_nop 1
	v_max_f32_e32 v32, 0, v24
	v_max_f32_e32 v33, 0, v25
	v_max_f32_e32 v28, 0, v28
	v_max_f32_e32 v29, 0, v29
	v_max_f32_e32 v30, 0, v30
	v_max_f32_e32 v31, 0, v31
	v_max_f32_e32 v34, 0, v26
	v_max_f32_e32 v35, 0, v27
	v_pk_mul_f32 v[24:25], v[28:29], v[28:29]
	v_pk_mul_f32 v[26:27], v[30:31], v[30:31]
	v_cvt_pk_bf16_f32 v24, v24, v25
	v_cvt_pk_bf16_f32 v25, v26, v27
	v_pk_mul_f32 v[26:27], v[32:33], v[32:33]
	v_pk_mul_f32 v[28:29], v[34:35], v[34:35]
	s_mov_b32 s7, 0x140000
	v_cvt_pk_bf16_f32 v26, v26, v27
	v_cvt_pk_bf16_f32 v27, v28, v29
	v_add_co_u32_e32 v28, vcc, s7, v140
	s_nop 0
	v_addc_co_u32_e32 v29, vcc, 0, v141, vcc
	global_store_dwordx4 v[28:29], v[24:27], off
	s_nop 1
	v_max_f32_e32 v24, 0, v16
	v_max_f32_e32 v25, 0, v17
	v_max_f32_e32 v20, 0, v20
	v_max_f32_e32 v21, 0, v21
	v_max_f32_e32 v22, 0, v22
	v_max_f32_e32 v23, 0, v23
	v_max_f32_e32 v26, 0, v18
	v_max_f32_e32 v27, 0, v19
	v_pk_mul_f32 v[16:17], v[20:21], v[20:21]
	v_pk_mul_f32 v[18:19], v[22:23], v[22:23]
	v_cvt_pk_bf16_f32 v16, v16, v17
	v_cvt_pk_bf16_f32 v17, v18, v19
	v_pk_mul_f32 v[18:19], v[24:25], v[24:25]
	v_pk_mul_f32 v[20:21], v[26:27], v[26:27]
	v_cvt_pk_bf16_f32 v18, v18, v19
	v_cvt_pk_bf16_f32 v19, v20, v21
	global_store_dwordx4 v[28:29], v[16:19], off offset:256
	s_nop 1
	v_max_f32_e32 v16, 0, v8
	v_max_f32_e32 v17, 0, v9
	v_max_f32_e32 v12, 0, v12
	v_max_f32_e32 v13, 0, v13
	v_max_f32_e32 v14, 0, v14
	v_max_f32_e32 v15, 0, v15
	v_max_f32_e32 v18, 0, v10
	v_max_f32_e32 v19, 0, v11
	v_pk_mul_f32 v[8:9], v[12:13], v[12:13]
	v_pk_mul_f32 v[10:11], v[14:15], v[14:15]
	v_cvt_pk_bf16_f32 v8, v8, v9
	v_cvt_pk_bf16_f32 v9, v10, v11
	v_pk_mul_f32 v[10:11], v[16:17], v[16:17]
	v_pk_mul_f32 v[12:13], v[18:19], v[18:19]
	s_mov_b32 s7, 0x160000
	v_cvt_pk_bf16_f32 v10, v10, v11
	v_cvt_pk_bf16_f32 v11, v12, v13
	v_add_co_u32_e32 v12, vcc, s7, v140
	s_nop 0
	v_addc_co_u32_e32 v13, vcc, 0, v141, vcc
	global_store_dwordx4 v[12:13], v[8:11], off
	s_nop 1
	v_max_f32_e32 v8, 0, v0
	v_max_f32_e32 v9, 0, v1
	v_max_f32_e32 v4, 0, v4
	v_max_f32_e32 v5, 0, v5
	v_max_f32_e32 v6, 0, v6
	v_max_f32_e32 v7, 0, v7
	v_max_f32_e32 v10, 0, v2
	v_max_f32_e32 v11, 0, v3
	v_pk_mul_f32 v[0:1], v[4:5], v[4:5]
	v_pk_mul_f32 v[2:3], v[6:7], v[6:7]
	v_cvt_pk_bf16_f32 v0, v0, v1
	v_cvt_pk_bf16_f32 v1, v2, v3
	v_pk_mul_f32 v[2:3], v[8:9], v[8:9]
	v_pk_mul_f32 v[4:5], v[10:11], v[10:11]
	v_cvt_pk_bf16_f32 v2, v2, v3
	v_cvt_pk_bf16_f32 v3, v4, v5
	global_store_dwordx4 v[12:13], v[0:3], off offset:256
	s_and_b64 vcc, exec, s[2:3]
	s_mov_b32 s46, s6
	s_mov_b32 s18, s8
	s_mov_b64 s[22:23], s[16:17]
	s_mov_b64 s[20:21], s[14:15]
	s_cbranch_vccz .LBB0_1027
	s_waitcnt vmcnt(0)
	s_cmpk_gt_u32 s26, 0xff
	s_cbranch_scc1 .LBB0_1034
	s_barrier

.LBB0_1053:
	v_cmp_lt_i64_e32 vcc, s[12:13], v[198:199]
	v_readlane_b32 s12, v254, 15
	v_readlane_b32 s13, v254, 16
	s_add_u32 s12, s12, s8
	s_addc_u32 s13, s13, s9
	s_and_b64 s[14:15], vcc, exec
	s_cselect_b32 s5, s13, s19
	s_cselect_b32 s7, s12, s18
	s_add_u32 s14, s27, s10
	s_addc_u32 s15, s28, s11
	s_and_b64 s[22:23], vcc, exec
	s_cselect_b32 s17, s15, s21
	s_cselect_b32 s64, s14, s20
	s_add_u32 s18, s18, 0x100080
	s_addc_u32 s19, s19, 0
	s_add_u32 s65, s20, 0x100
	v_mov_b32_e32 v0, 0
	s_addc_u32 s66, s21, 0
	s_mov_b32 s67, -2
	v_mov_b64_e32 v[0:1], 0
	v_mov_b64_e32 v[2:3], 0
	v_mov_b64_e32 v[4:5], 0
	v_mov_b64_e32 v[6:7], 0
	v_mov_b64_e32 v[8:9], 0
	v_mov_b64_e32 v[10:11], 0
	v_mov_b64_e32 v[12:13], 0
	v_mov_b64_e32 v[14:15], 0
	v_mov_b64_e32 v[16:17], 0
	v_mov_b64_e32 v[18:19], 0
	v_mov_b64_e32 v[20:21], 0
	v_mov_b64_e32 v[22:23], 0
	v_mov_b64_e32 v[24:25], 0
	v_mov_b64_e32 v[26:27], 0
	v_mov_b64_e32 v[28:29], 0
	v_mov_b64_e32 v[30:31], 0
	v_mov_b64_e32 v[32:33], 0
	v_mov_b64_e32 v[34:35], 0
	v_mov_b64_e32 v[36:37], 0
	v_mov_b64_e32 v[38:39], 0
	v_mov_b64_e32 v[40:41], 0
	v_mov_b64_e32 v[42:43], 0
	v_mov_b64_e32 v[44:45], 0
	v_mov_b64_e32 v[46:47], 0
	v_mov_b64_e32 v[48:49], 0
	v_mov_b64_e32 v[50:51], 0
	v_mov_b64_e32 v[52:53], 0
	v_mov_b64_e32 v[54:55], 0
	v_mov_b64_e32 v[56:57], 0
	v_mov_b64_e32 v[58:59], 0
	v_mov_b64_e32 v[60:61], 0
	v_mov_b64_e32 v[62:63], 0
	v_mov_b64_e32 v[64:65], 0
	v_mov_b64_e32 v[66:67], 0
	v_mov_b64_e32 v[68:69], 0
	v_mov_b64_e32 v[70:71], 0
	v_mov_b64_e32 v[72:73], 0
	v_mov_b64_e32 v[74:75], 0
	v_mov_b64_e32 v[76:77], 0
	v_mov_b64_e32 v[78:79], 0
	v_mov_b64_e32 v[80:81], 0
	v_mov_b64_e32 v[82:83], 0
	v_mov_b64_e32 v[84:85], 0
	v_mov_b64_e32 v[86:87], 0
	v_mov_b64_e32 v[88:89], 0
	v_mov_b64_e32 v[90:91], 0
	v_mov_b64_e32 v[92:93], 0
	v_mov_b64_e32 v[94:95], 0
	v_mov_b64_e32 v[96:97], 0
	v_mov_b64_e32 v[98:99], 0
	v_mov_b64_e32 v[100:101], 0
	v_mov_b64_e32 v[102:103], 0
	v_mov_b64_e32 v[104:105], 0
	v_mov_b64_e32 v[106:107], 0
	v_mov_b64_e32 v[108:109], 0
	v_mov_b64_e32 v[110:111], 0
	v_mov_b64_e32 v[112:113], 0
	v_mov_b64_e32 v[114:115], 0
	v_mov_b64_e32 v[116:117], 0
	v_mov_b64_e32 v[118:119], 0
	v_mov_b64_e32 v[128:129], 0
	v_mov_b64_e32 v[130:131], 0
	v_mov_b64_e32 v[132:133], 0
	v_mov_b64_e32 v[134:135], 0
